# v89 + p34_plain_safe2: P3 merged / P4 xmb+SSQ write-back and read from the producer XCD's L2; placement check folded into barrier 0's existing XCNT scan load; full write-back fallback
# baseline (speedup 1.0000x reference)
.LBB0_2:
	s_or_b64 exec, exec, s[4:5]
	s_load_dwordx16 s[40:55], s[0:1], 0x0
	s_waitcnt lgkmcnt(0)
	s_barrier
	s_add_u32 s88, s80, 0x2380000
	s_getreg_b32 s4, hwreg(HW_REG_XCC_ID, 0, 4)
	s_addc_u32 s89, s81, 0
	s_and_b32 s87, s4, 15
	s_and_saveexec_b64 s[4:5], s[94:95]
	s_cbranch_execz .LBB0_5
	s_mov_b64 s[6:7], exec
	v_mbcnt_lo_u32_b32 v1, s6, 0
	v_mbcnt_hi_u32_b32 v1, s7, v1
	v_cmp_eq_u32_e32 vcc, 0, v1
	s_and_b64 s[8:9], exec, vcc
	s_mov_b64 exec, s[8:9]
	s_cbranch_execz .LBB0_5
	s_lshl_b32 s8, s87, 8
	s_bcnt1_i32_b64 s6, s[6:7]
	v_mov_b32_e32 v1, s8
	v_mov_b32_e32 v2, s6
	global_atomic_add v1, v2, s[88:89] offset:1024
	s_and_b32 s9, s2, 7
	s_lshl_b32 s9, s9, 2
	s_add_i32 s9, s9, 0x100
	s_add_i32 s8, s87, 1
	v_mov_b32_e32 v3, s9
	v_mov_b32_e32 v4, s8
	s_sub_i32 s8, 16, s87
	v_mov_b32_e32 v5, s8
	global_atomic_umax v3, v4, s[88:89]
	global_atomic_umax v3, v5, s[88:89] offset:32

.LBB0_35:
	s_waitcnt lgkmcnt(0)
	v_writelane_b32 v255, s56, 9
	s_cmp_gt_i32 s83, 1
	s_cselect_b64 s[0:1], -1, 0
	v_writelane_b32 v255, s57, 10
	v_writelane_b32 v255, s58, 11
	v_writelane_b32 v255, s59, 12
	v_writelane_b32 v255, s60, 13
	v_writelane_b32 v255, s61, 14
	v_writelane_b32 v255, s62, 15
	v_writelane_b32 v255, s63, 16
	v_writelane_b32 v255, s64, 17
	v_writelane_b32 v255, s65, 18
	v_writelane_b32 v255, s66, 19
	v_writelane_b32 v255, s67, 20
	v_writelane_b32 v255, s68, 21
	v_writelane_b32 v255, s69, 22
	s_and_b64 s[4:5], s[4:5], s[0:1]
	v_writelane_b32 v255, s70, 23
	s_andn2_b64 vcc, exec, s[4:5]
	v_writelane_b32 v255, s71, 24
	s_cbranch_vccnz .LBB0_89
	s_waitcnt vmcnt(0)
	s_barrier
	s_and_saveexec_b64 s[4:5], s[94:95]
	s_cbranch_execz .LBB0_88
	s_add_u32 s6, s80, 0x2380000
	s_addc_u32 s7, s81, 0
	s_mov_b64 exec, 0xffffffff
	v_mbcnt_lo_u32_b32 v4, -1, 0
	v_lshlrev_b32_e32 v1, 2, v4
	v_add_u32_e32 v1, 0xc0, v1
	v_lshlrev_b32_e32 v2, 8, v4
	v_add_u32_e32 v2, 0x400, v2
	v_cmp_gt_u32_e32 vcc, 16, v4
	s_nop 1
	v_cndmask_b32_e32 v2, v1, v2, vcc
	s_mov_b32 s10, 0

.Lxb0_ok:
	s_mov_b32 s32, 0
	v_readlane_b32 s8, v3, 16
	v_readlane_b32 s9, v3, 24
	s_add_u32 s8, s8, s9
	s_cmp_lg_u32 s8, 17
	s_cselect_b32 s8, 1, 0
	s_or_b32 s32, s32, s8
	v_readlane_b32 s8, v3, 17
	v_readlane_b32 s9, v3, 25
	s_add_u32 s8, s8, s9
	s_cmp_lg_u32 s8, 17
	s_cselect_b32 s8, 1, 0
	s_or_b32 s32, s32, s8
	v_readlane_b32 s8, v3, 18
	v_readlane_b32 s9, v3, 26
	s_add_u32 s8, s8, s9
	s_cmp_lg_u32 s8, 17
	s_cselect_b32 s8, 1, 0
	s_or_b32 s32, s32, s8
	v_readlane_b32 s8, v3, 19
	v_readlane_b32 s9, v3, 27
	s_add_u32 s8, s8, s9
	s_cmp_lg_u32 s8, 17
	s_cselect_b32 s8, 1, 0
	s_or_b32 s32, s32, s8
	v_readlane_b32 s8, v3, 20
	v_readlane_b32 s9, v3, 28
	s_add_u32 s8, s8, s9
	s_cmp_lg_u32 s8, 17
	s_cselect_b32 s8, 1, 0
	s_or_b32 s32, s32, s8
	v_readlane_b32 s8, v3, 21
	v_readlane_b32 s9, v3, 29
	s_add_u32 s8, s8, s9
	s_cmp_lg_u32 s8, 17
	s_cselect_b32 s8, 1, 0
	s_or_b32 s32, s32, s8
	v_readlane_b32 s8, v3, 22
	v_readlane_b32 s9, v3, 30
	s_add_u32 s8, s8, s9
	s_cmp_lg_u32 s8, 17
	s_cselect_b32 s8, 1, 0
	s_or_b32 s32, s32, s8
	v_readlane_b32 s8, v3, 23
	v_readlane_b32 s9, v3, 31
	s_add_u32 s8, s8, s9
	s_cmp_lg_u32 s8, 17
	s_cselect_b32 s8, 1, 0
	s_or_b32 s32, s32, s8
	s_cmp_lg_u32 s3, 0x100
	s_cselect_b32 s8, 1, 0
	s_or_b32 s32, s32, s8
	s_mov_b64 exec, 0xffff
	v_cmp_ne_u32_e32 vcc, 0, v3
	s_nop 3
	v_readlane_b32 s16, v3, s87
	s_bcnt1_i32_b64 s9, vcc
	s_max_u32 s16, s16, 1
	s_max_u32 s9, s9, 1
	s_mov_b64 exec, 1
	v_mov_b32_e32 v1, 0x23ff0
	v_mov_b32_e32 v2, s16
	v_mov_b32_e32 v3, s9
	ds_write_b32 v1, v2
	ds_write_b32 v1, v3 offset:4
	s_waitcnt lgkmcnt(0)
	v_mov_b32_e32 v1, 0x23ff0
	ds_read_b32 v2, v1
	ds_read_b32 v3, v1 offset:4
	s_add_u32 s6, s80, 0x2380000
	s_addc_u32 s7, s81, 0
	s_lshl_b32 s8, s87, 8
	s_add_i32 s9, s8, 0x1400
	s_add_i32 s8, s8, 0x2400
	v_mov_b32_e32 v4, s9
	v_mov_b32_e32 v5, 1
	global_atomic_add v6, v4, v5, s[6:7] sc0
	buffer_inv sc1
	s_waitcnt vmcnt(0) lgkmcnt(0)
	v_readfirstlane_b32 s10, v6
	v_readfirstlane_b32 s11, v2
	v_readfirstlane_b32 s16, v3
	s_add_i32 s10, s10, 1
	s_mul_i32 s11, s11, 1
	s_cmp_lg_u32 s10, s11
	s_cbranch_scc1 .Lxb_nl_0
	buffer_wbl2 sc1
	s_waitcnt vmcnt(0)
	v_mov_b32_e32 v4, 0x3400
	global_atomic_add v6, v4, v5, s[6:7] sc0
	s_waitcnt vmcnt(0)
	v_readfirstlane_b32 s10, v6
	s_add_i32 s10, s10, 1
	s_mul_i32 s16, s16, 1
	s_cmp_lg_u32 s10, s16
	s_cbranch_scc1 .Lxb_nl_0
	v_mov_b32_e32 v4, 0x2400
	global_atomic_add v4, v5, s[6:7]
	global_atomic_add v4, v5, s[6:7] offset:256
	global_atomic_add v4, v5, s[6:7] offset:512
	global_atomic_add v4, v5, s[6:7] offset:768
	global_atomic_add v4, v5, s[6:7] offset:1024
	global_atomic_add v4, v5, s[6:7] offset:1280
	global_atomic_add v4, v5, s[6:7] offset:1536
	global_atomic_add v4, v5, s[6:7] offset:1792
	global_atomic_add v4, v5, s[6:7] offset:2048
	global_atomic_add v4, v5, s[6:7] offset:2304
	global_atomic_add v4, v5, s[6:7] offset:2560
	global_atomic_add v4, v5, s[6:7] offset:2816
	global_atomic_add v4, v5, s[6:7] offset:3072
	global_atomic_add v4, v5, s[6:7] offset:3328
	global_atomic_add v4, v5, s[6:7] offset:3584
	global_atomic_add v4, v5, s[6:7] offset:3840
	s_branch .Lxb_done_0
